# v5_hoist2
# speedup vs baseline: 1.0038x; 1.0038x over previous
; __device__ __forceinline__ float fdiv(float a, float b) { return a * __builtin_amdgcn_rcpf(b); }
; __device__ __forceinline__ void gemm_tile(const Params& P, const GArgs& ga, const TileDesc& td, int wid_s) {
;     ...
;   if (mode == M_GU) {
;     LOAD_RSV
;     unsigned* __restrict__ G = reinterpret_cast<unsigned*>(WSU(G) + (size_t)rbase * FF + (bcol >> 1) + (x4 >> 1));
;     static_for<32>([&](auto ic) __attribute__((always_inline)) {
;       EPI_IDX;
;       const float rs = rsv[idx];
;       float g0 = rs * acc[ai][0][m][0][j], u0 = rs * acc[ai][0][m][1][j];
;       float g1 = rs * acc[ai][1][m][0][j], u1 = rs * acc[ai][1][m][1][j];
;       __builtin_nontemporal_store(pack2(fdiv(g0 * u0, 1.f + __expf(-g0)), fdiv(g1 * u1, 1.f + __expf(-g1))), G + (size_t)rl * (FF / 2));
;       if constexpr ((idx & 7) == 7) __builtin_amdgcn_sched_barrier(0);
;     });
.LBB0_748:
	s_and_b64 vcc, exec, s[84:85]
	s_cbranch_vccz .LBB0_290
	v_and_b32_e32 v198, 15, v200
	v_and_b32_e32 v199, 0xc0, v200
	v_lshl_or_b32 v198, v198, 2, v199
	s_lshl_b32 s0, s15, 8
	v_mov_b32_e32 v199, 0x2c00
	v_mad_u32_u24 v198, v162, v199, v198
	v_mov_b32_e32 v199, s17
	v_add_u32_e32 v198, s0, v198
	s_waitcnt vmcnt(15)
	v_fmamk_f32 v204, v204, 0x3a000000, v199
	v_fmamk_f32 v205, v205, 0x3a000000, v199
	v_fmamk_f32 v206, v206, 0x3a000000, v199
	v_fmamk_f32 v207, v207, 0x3a000000, v199
	v_rsq_f32_e32 v130, v204
	v_rsq_f32_e32 v131, v205
	v_rsq_f32_e32 v132, v206
	v_rsq_f32_e32 v133, v207
	s_waitcnt vmcnt(14)
	v_fmamk_f32 v208, v208, 0x3a000000, v199
	v_fmamk_f32 v209, v209, 0x3a000000, v199
	v_fmamk_f32 v210, v210, 0x3a000000, v199
	v_fmamk_f32 v211, v211, 0x3a000000, v199
	v_rsq_f32_e32 v134, v208
	v_rsq_f32_e32 v135, v209
	v_rsq_f32_e32 v136, v210
	v_rsq_f32_e32 v137, v211
	v_mul_f32_e32 v130, 0xbfb8aa3b, v130
	v_mul_f32_e32 v131, 0xbfb8aa3b, v131
	v_mul_f32_e32 v132, 0xbfb8aa3b, v132
	v_mul_f32_e32 v133, 0xbfb8aa3b, v133
	s_waitcnt vmcnt(13)
	v_fmamk_f32 v212, v212, 0x3a000000, v199
	v_fmamk_f32 v213, v213, 0x3a000000, v199
	v_fmamk_f32 v214, v214, 0x3a000000, v199
	v_fmamk_f32 v215, v215, 0x3a000000, v199
	v_rsq_f32_e32 v138, v212
	v_rsq_f32_e32 v139, v213
	v_rsq_f32_e32 v140, v214
	v_rsq_f32_e32 v141, v215
	v_mul_f32_e32 v134, 0xbfb8aa3b, v134
	v_mul_f32_e32 v135, 0xbfb8aa3b, v135
	v_mul_f32_e32 v136, 0xbfb8aa3b, v136
	v_mul_f32_e32 v137, 0xbfb8aa3b, v137
	s_waitcnt vmcnt(12)
	v_fmamk_f32 v216, v216, 0x3a000000, v199
	v_fmamk_f32 v217, v217, 0x3a000000, v199
	v_fmamk_f32 v218, v218, 0x3a000000, v199
	v_fmamk_f32 v219, v219, 0x3a000000, v199
	v_rsq_f32_e32 v142, v216
	v_rsq_f32_e32 v143, v217
	v_rsq_f32_e32 v144, v218
	v_rsq_f32_e32 v145, v219
	v_mul_f32_e32 v138, 0xbfb8aa3b, v138
	v_mul_f32_e32 v139, 0xbfb8aa3b, v139
	v_mul_f32_e32 v140, 0xbfb8aa3b, v140
	v_mul_f32_e32 v141, 0xbfb8aa3b, v141
	s_waitcnt vmcnt(11)
	v_fmamk_f32 v220, v220, 0x3a000000, v199
	v_fmamk_f32 v221, v221, 0x3a000000, v199
	v_fmamk_f32 v222, v222, 0x3a000000, v199
	v_fmamk_f32 v223, v223, 0x3a000000, v199
	v_rsq_f32_e32 v146, v220
	v_rsq_f32_e32 v147, v221
	v_rsq_f32_e32 v148, v222
	v_rsq_f32_e32 v149, v223
	v_mul_f32_e32 v142, 0xbfb8aa3b, v142
	v_mul_f32_e32 v143, 0xbfb8aa3b, v143
	v_mul_f32_e32 v144, 0xbfb8aa3b, v144
	v_mul_f32_e32 v145, 0xbfb8aa3b, v145
	s_waitcnt vmcnt(10)
	v_fmamk_f32 v224, v224, 0x3a000000, v199
	v_fmamk_f32 v225, v225, 0x3a000000, v199
	v_fmamk_f32 v226, v226, 0x3a000000, v199
	v_fmamk_f32 v227, v227, 0x3a000000, v199
	v_rsq_f32_e32 v150, v224
	v_rsq_f32_e32 v151, v225
	v_rsq_f32_e32 v152, v226
	v_rsq_f32_e32 v153, v227
	v_mul_f32_e32 v146, 0xbfb8aa3b, v146
	v_mul_f32_e32 v147, 0xbfb8aa3b, v147
	v_mul_f32_e32 v148, 0xbfb8aa3b, v148
	v_mul_f32_e32 v149, 0xbfb8aa3b, v149
	s_waitcnt vmcnt(9)
	v_fmamk_f32 v170, v170, 0x3a000000, v199
	v_fmamk_f32 v171, v171, 0x3a000000, v199
	v_fmamk_f32 v172, v172, 0x3a000000, v199
	v_fmamk_f32 v173, v173, 0x3a000000, v199
	v_rsq_f32_e32 v154, v170
	v_rsq_f32_e32 v155, v171
	v_rsq_f32_e32 v156, v172
	v_rsq_f32_e32 v157, v173
	v_mul_f32_e32 v150, 0xbfb8aa3b, v150
	v_mul_f32_e32 v151, 0xbfb8aa3b, v151
	v_mul_f32_e32 v152, 0xbfb8aa3b, v152
	v_mul_f32_e32 v153, 0xbfb8aa3b, v153
	s_waitcnt vmcnt(8)
	v_fmamk_f32 v174, v174, 0x3a000000, v199
	v_fmamk_f32 v175, v175, 0x3a000000, v199
	v_fmamk_f32 v176, v176, 0x3a000000, v199
	v_fmamk_f32 v177, v177, 0x3a000000, v199
	v_rsq_f32_e32 v158, v174
	v_rsq_f32_e32 v159, v175
	v_rsq_f32_e32 v160, v176
	v_rsq_f32_e32 v161, v177
	v_mul_f32_e32 v154, 0xbfb8aa3b, v154
	v_mul_f32_e32 v155, 0xbfb8aa3b, v155
	v_mul_f32_e32 v156, 0xbfb8aa3b, v156
	v_mul_f32_e32 v157, 0xbfb8aa3b, v157
	s_nop 0
	v_mul_f32_e32 v158, 0xbfb8aa3b, v158
	v_mul_f32_e32 v159, 0xbfb8aa3b, v159
	v_mul_f32_e32 v160, 0xbfb8aa3b, v160
	v_mul_f32_e32 v161, 0xbfb8aa3b, v161
	v_mul_f32_e32 v178, v114, v130
	v_mul_f32_e32 v179, v126, v130
	v_mul_f32_e32 v180, v115, v131
	v_mul_f32_e32 v181, v127, v131
	v_mul_f32_e32 v182, v116, v132
	v_mul_f32_e32 v183, v128, v132
	v_mul_f32_e32 v184, v117, v133
	v_mul_f32_e32 v185, v129, v133
	v_exp_f32_e32 v178, v178
	v_exp_f32_e32 v179, v179
	v_exp_f32_e32 v180, v180
	v_exp_f32_e32 v181, v181
	v_exp_f32_e32 v182, v182
	v_exp_f32_e32 v183, v183
	v_exp_f32_e32 v184, v184
	v_exp_f32_e32 v185, v185
	v_mul_f32_e32 v186, v114, v118
	v_mul_f32_e32 v187, v126, v122
	v_mul_f32_e32 v188, v115, v119
	v_mul_f32_e32 v189, v127, v123
	v_mul_f32_e32 v190, v116, v120
	v_mul_f32_e32 v191, v128, v124
	v_mul_f32_e32 v192, v117, v121
	v_mul_f32_e32 v193, v129, v125
	v_fma_f32 v178, v178, v204, v204
	v_fma_f32 v179, v179, v204, v204
	v_fma_f32 v180, v180, v205, v205
	v_fma_f32 v181, v181, v205, v205
	v_fma_f32 v182, v182, v206, v206
	v_fma_f32 v183, v183, v206, v206
	v_fma_f32 v184, v184, v207, v207
	v_fma_f32 v185, v185, v207, v207
	v_rcp_f32_e32 v178, v178
	v_rcp_f32_e32 v179, v179
	v_rcp_f32_e32 v180, v180
	v_rcp_f32_e32 v181, v181
	v_rcp_f32_e32 v182, v182
	v_rcp_f32_e32 v183, v183
	v_rcp_f32_e32 v184, v184
	v_rcp_f32_e32 v185, v185
	v_mul_f32_e32 v186, v186, v178
	v_mul_f32_e32 v187, v187, v179
	v_mul_f32_e32 v188, v188, v180
	v_mul_f32_e32 v189, v189, v181
	s_add_u32 s4, s24, 0x0
	s_addc_u32 s5, s25, 0
	v_mul_f32_e32 v190, v190, v182
	v_mul_f32_e32 v191, v191, v183
	v_mul_f32_e32 v192, v192, v184
	v_mul_f32_e32 v193, v193, v185
	v_cvt_pk_bf16_f32 v194, v186, v187
	v_cvt_pk_bf16_f32 v195, v188, v189
	v_cvt_pk_bf16_f32 v196, v190, v191
	v_cvt_pk_bf16_f32 v197, v192, v193
	global_store_dword v198, v194, s[4:5]
	s_add_u32 s4, s4, 0x2c00
	s_addc_u32 s5, s5, 0
	global_store_dword v198, v195, s[4:5]
; __device__ __forceinline__ float fdiv(float a, float b) { return a * __builtin_amdgcn_rcpf(b); }
; __device__ __forceinline__ void gemm_tile(const Params& P, const GArgs& ga, const TileDesc& td, int wid_s) {
;     ...
;     static_for<32>([&](auto ic) __attribute__((always_inline)) {
;       EPI_IDX;
;       const float rs = rsv[idx];
;       float g0 = rs * acc[ai][0][m][0][j], u0 = rs * acc[ai][0][m][1][j];
;       float g1 = rs * acc[ai][1][m][0][j], u1 = rs * acc[ai][1][m][1][j];
;       __builtin_nontemporal_store(pack2(fdiv(g0 * u0, 1.f + __expf(-g0)), fdiv(g1 * u1, 1.f + __expf(-g1))), G + (size_t)rl * (FF / 2));
;       if constexpr ((idx & 7) == 7) __builtin_amdgcn_sched_barrier(0);
;     });
	s_add_u32 s4, s4, 0x2c00
	s_addc_u32 s5, s5, 0
	global_store_dword v198, v196, s[4:5]
	s_add_u32 s4, s4, 0x2c00
	s_addc_u32 s5, s5, 0
	global_store_dword v198, v197, s[4:5]
	v_mul_f32_e32 v178, v98, v134
	v_mul_f32_e32 v179, v110, v134
	v_mul_f32_e32 v180, v99, v135
	v_mul_f32_e32 v181, v111, v135
	v_mul_f32_e32 v182, v100, v136
	v_mul_f32_e32 v183, v112, v136
	v_mul_f32_e32 v184, v101, v137
	v_mul_f32_e32 v185, v113, v137
	v_exp_f32_e32 v178, v178
	v_exp_f32_e32 v179, v179
	v_exp_f32_e32 v180, v180
	v_exp_f32_e32 v181, v181
	v_exp_f32_e32 v182, v182
	v_exp_f32_e32 v183, v183
	v_exp_f32_e32 v184, v184
	v_exp_f32_e32 v185, v185
	v_mul_f32_e32 v186, v98, v102
	v_mul_f32_e32 v187, v110, v106
	v_mul_f32_e32 v188, v99, v103
	v_mul_f32_e32 v189, v111, v107
	v_mul_f32_e32 v190, v100, v104
	v_mul_f32_e32 v191, v112, v108
	v_mul_f32_e32 v192, v101, v105
	v_mul_f32_e32 v193, v113, v109
	v_fma_f32 v178, v178, v208, v208
	v_fma_f32 v179, v179, v208, v208
	v_fma_f32 v180, v180, v209, v209
	v_fma_f32 v181, v181, v209, v209
	v_fma_f32 v182, v182, v210, v210
	v_fma_f32 v183, v183, v210, v210
	v_fma_f32 v184, v184, v211, v211
	v_fma_f32 v185, v185, v211, v211
	v_rcp_f32_e32 v178, v178
	v_rcp_f32_e32 v179, v179
	v_rcp_f32_e32 v180, v180
	v_rcp_f32_e32 v181, v181
	v_rcp_f32_e32 v182, v182
	v_rcp_f32_e32 v183, v183
	v_rcp_f32_e32 v184, v184
	v_rcp_f32_e32 v185, v185
	v_mul_f32_e32 v186, v186, v178
	v_mul_f32_e32 v187, v187, v179
	v_mul_f32_e32 v188, v188, v180
	v_mul_f32_e32 v189, v189, v181
	s_add_u32 s4, s24, 0x2c000
	s_addc_u32 s5, s25, 0
	v_mul_f32_e32 v190, v190, v182
	v_mul_f32_e32 v191, v191, v183
	v_mul_f32_e32 v192, v192, v184
	v_mul_f32_e32 v193, v193, v185
	v_cvt_pk_bf16_f32 v194, v186, v187
	v_cvt_pk_bf16_f32 v195, v188, v189
	v_cvt_pk_bf16_f32 v196, v190, v191
	v_cvt_pk_bf16_f32 v197, v192, v193
	global_store_dword v198, v194, s[4:5]
	s_add_u32 s4, s4, 0x2c00
	s_addc_u32 s5, s5, 0
	global_store_dword v198, v195, s[4:5]
	s_add_u32 s4, s4, 0x2c00
	s_addc_u32 s5, s5, 0
	global_store_dword v198, v196, s[4:5]
	s_add_u32 s4, s4, 0x2c00
	s_addc_u32 s5, s5, 0
	global_store_dword v198, v197, s[4:5]
	v_mul_f32_e32 v178, v82, v138
	v_mul_f32_e32 v179, v94, v138
	v_mul_f32_e32 v180, v83, v139
	v_mul_f32_e32 v181, v95, v139
	v_mul_f32_e32 v182, v84, v140
	v_mul_f32_e32 v183, v96, v140
	v_mul_f32_e32 v184, v85, v141
	v_mul_f32_e32 v185, v97, v141
	v_exp_f32_e32 v178, v178
	v_exp_f32_e32 v179, v179
	v_exp_f32_e32 v180, v180
	v_exp_f32_e32 v181, v181
	v_exp_f32_e32 v182, v182
	v_exp_f32_e32 v183, v183
	v_exp_f32_e32 v184, v184
	v_exp_f32_e32 v185, v185
	v_mul_f32_e32 v186, v82, v86
	v_mul_f32_e32 v187, v94, v90
	v_mul_f32_e32 v188, v83, v87
	v_mul_f32_e32 v189, v95, v91
	v_mul_f32_e32 v190, v84, v88
	v_mul_f32_e32 v191, v96, v92
	v_mul_f32_e32 v192, v85, v89
	v_mul_f32_e32 v193, v97, v93
	v_fma_f32 v178, v178, v212, v212
	v_fma_f32 v179, v179, v212, v212
	v_fma_f32 v180, v180, v213, v213
	v_fma_f32 v181, v181, v213, v213
	v_fma_f32 v182, v182, v214, v214
	v_fma_f32 v183, v183, v214, v214
	v_fma_f32 v184, v184, v215, v215
	v_fma_f32 v185, v185, v215, v215
	v_rcp_f32_e32 v178, v178
	v_rcp_f32_e32 v179, v179
	v_rcp_f32_e32 v180, v180
	v_rcp_f32_e32 v181, v181
	v_rcp_f32_e32 v182, v182
	v_rcp_f32_e32 v183, v183
	v_rcp_f32_e32 v184, v184
	v_rcp_f32_e32 v185, v185
	v_mul_f32_e32 v186, v186, v178
	v_mul_f32_e32 v187, v187, v179
	v_mul_f32_e32 v188, v188, v180
	v_mul_f32_e32 v189, v189, v181
	s_add_u32 s4, s24, 0x58000
	s_addc_u32 s5, s25, 0
	v_mul_f32_e32 v190, v190, v182
	v_mul_f32_e32 v191, v191, v183
	v_mul_f32_e32 v192, v192, v184
	v_mul_f32_e32 v193, v193, v185
	v_cvt_pk_bf16_f32 v194, v186, v187
	v_cvt_pk_bf16_f32 v195, v188, v189
	v_cvt_pk_bf16_f32 v196, v190, v191
	v_cvt_pk_bf16_f32 v197, v192, v193
	global_store_dword v198, v194, s[4:5]
	s_add_u32 s4, s4, 0x2c00
	s_addc_u32 s5, s5, 0
	global_store_dword v198, v195, s[4:5]
	s_add_u32 s4, s4, 0x2c00
	s_addc_u32 s5, s5, 0
	global_store_dword v198, v196, s[4:5]
	s_add_u32 s4, s4, 0x2c00
	s_addc_u32 s5, s5, 0
	global_store_dword v198, v197, s[4:5]
	v_mul_f32_e32 v178, v66, v142
	v_mul_f32_e32 v179, v78, v142
	v_mul_f32_e32 v180, v67, v143
	v_mul_f32_e32 v181, v79, v143
	v_mul_f32_e32 v182, v68, v144
	v_mul_f32_e32 v183, v80, v144
	v_mul_f32_e32 v184, v69, v145
	v_mul_f32_e32 v185, v81, v145
	v_exp_f32_e32 v178, v178
	v_exp_f32_e32 v179, v179
	v_exp_f32_e32 v180, v180
	v_exp_f32_e32 v181, v181
	v_exp_f32_e32 v182, v182
	v_exp_f32_e32 v183, v183
	v_exp_f32_e32 v184, v184
	v_exp_f32_e32 v185, v185
	v_mul_f32_e32 v186, v66, v70
	v_mul_f32_e32 v187, v78, v74
	v_mul_f32_e32 v188, v67, v71
	v_mul_f32_e32 v189, v79, v75
	v_mul_f32_e32 v190, v68, v72
	v_mul_f32_e32 v191, v80, v76
	v_mul_f32_e32 v192, v69, v73
	v_mul_f32_e32 v193, v81, v77
	v_fma_f32 v178, v178, v216, v216
	v_fma_f32 v179, v179, v216, v216
	v_fma_f32 v180, v180, v217, v217
	v_fma_f32 v181, v181, v217, v217
	v_fma_f32 v182, v182, v218, v218
	v_fma_f32 v183, v183, v218, v218
	v_fma_f32 v184, v184, v219, v219
	v_fma_f32 v185, v185, v219, v219
	v_rcp_f32_e32 v178, v178
	v_rcp_f32_e32 v179, v179
	v_rcp_f32_e32 v180, v180
	v_rcp_f32_e32 v181, v181
	v_rcp_f32_e32 v182, v182
	v_rcp_f32_e32 v183, v183
	v_rcp_f32_e32 v184, v184
	v_rcp_f32_e32 v185, v185
	v_mul_f32_e32 v186, v186, v178
	v_mul_f32_e32 v187, v187, v179
	v_mul_f32_e32 v188, v188, v180
	v_mul_f32_e32 v189, v189, v181
	s_add_u32 s4, s24, 0x84000
	s_addc_u32 s5, s25, 0
	v_mul_f32_e32 v190, v190, v182
	v_mul_f32_e32 v191, v191, v183
	v_mul_f32_e32 v192, v192, v184
	v_mul_f32_e32 v193, v193, v185
	v_cvt_pk_bf16_f32 v194, v186, v187
	v_cvt_pk_bf16_f32 v195, v188, v189
	v_cvt_pk_bf16_f32 v196, v190, v191
; __device__ __forceinline__ float fdiv(float a, float b) { return a * __builtin_amdgcn_rcpf(b); }
; __device__ __forceinline__ void gemm_tile(const Params& P, const GArgs& ga, const TileDesc& td, int wid_s) {
;     ...
;     static_for<32>([&](auto ic) __attribute__((always_inline)) {
;       EPI_IDX;
;       const float rs = rsv[idx];
;       float g0 = rs * acc[ai][0][m][0][j], u0 = rs * acc[ai][0][m][1][j];
;       float g1 = rs * acc[ai][1][m][0][j], u1 = rs * acc[ai][1][m][1][j];
;       __builtin_nontemporal_store(pack2(fdiv(g0 * u0, 1.f + __expf(-g0)), fdiv(g1 * u1, 1.f + __expf(-g1))), G + (size_t)rl * (FF / 2));
;       if constexpr ((idx & 7) == 7) __builtin_amdgcn_sched_barrier(0);
;     });
	v_cvt_pk_bf16_f32 v197, v192, v193
	global_store_dword v198, v194, s[4:5]
	s_add_u32 s4, s4, 0x2c00
	s_addc_u32 s5, s5, 0
	global_store_dword v198, v195, s[4:5]
	s_add_u32 s4, s4, 0x2c00
	s_addc_u32 s5, s5, 0
	global_store_dword v198, v196, s[4:5]
	s_add_u32 s4, s4, 0x2c00
	s_addc_u32 s5, s5, 0
	global_store_dword v198, v197, s[4:5]
	v_mul_f32_e32 v178, v50, v146
	v_mul_f32_e32 v179, v62, v146
	v_mul_f32_e32 v180, v51, v147
	v_mul_f32_e32 v181, v63, v147
	v_mul_f32_e32 v182, v52, v148
	v_mul_f32_e32 v183, v64, v148
	v_mul_f32_e32 v184, v53, v149
	v_mul_f32_e32 v185, v65, v149
	v_exp_f32_e32 v178, v178
	v_exp_f32_e32 v179, v179
	v_exp_f32_e32 v180, v180
	v_exp_f32_e32 v181, v181
	v_exp_f32_e32 v182, v182
	v_exp_f32_e32 v183, v183
	v_exp_f32_e32 v184, v184
	v_exp_f32_e32 v185, v185
	v_mul_f32_e32 v186, v50, v54
	v_mul_f32_e32 v187, v62, v58
	v_mul_f32_e32 v188, v51, v55
	v_mul_f32_e32 v189, v63, v59
	v_mul_f32_e32 v190, v52, v56
	v_mul_f32_e32 v191, v64, v60
	v_mul_f32_e32 v192, v53, v57
	v_mul_f32_e32 v193, v65, v61
	v_fma_f32 v178, v178, v220, v220
	v_fma_f32 v179, v179, v220, v220
	v_fma_f32 v180, v180, v221, v221
	v_fma_f32 v181, v181, v221, v221
	v_fma_f32 v182, v182, v222, v222
	v_fma_f32 v183, v183, v222, v222
	v_fma_f32 v184, v184, v223, v223
	v_fma_f32 v185, v185, v223, v223
	v_rcp_f32_e32 v178, v178
	v_rcp_f32_e32 v179, v179
	v_rcp_f32_e32 v180, v180
	v_rcp_f32_e32 v181, v181
	v_rcp_f32_e32 v182, v182
	v_rcp_f32_e32 v183, v183
	v_rcp_f32_e32 v184, v184
	v_rcp_f32_e32 v185, v185
	v_mul_f32_e32 v186, v186, v178
	v_mul_f32_e32 v187, v187, v179
	v_mul_f32_e32 v188, v188, v180
	v_mul_f32_e32 v189, v189, v181
	s_add_u32 s4, s24, 0x160000
	s_addc_u32 s5, s25, 0
	v_mul_f32_e32 v190, v190, v182
	v_mul_f32_e32 v191, v191, v183
	v_mul_f32_e32 v192, v192, v184
	v_mul_f32_e32 v193, v193, v185
	v_cvt_pk_bf16_f32 v194, v186, v187
	v_cvt_pk_bf16_f32 v195, v188, v189
	v_cvt_pk_bf16_f32 v196, v190, v191
	v_cvt_pk_bf16_f32 v197, v192, v193
	global_store_dword v198, v194, s[4:5]
	s_add_u32 s4, s4, 0x2c00
	s_addc_u32 s5, s5, 0
	global_store_dword v198, v195, s[4:5]
	s_add_u32 s4, s4, 0x2c00
	s_addc_u32 s5, s5, 0
	global_store_dword v198, v196, s[4:5]
	s_add_u32 s4, s4, 0x2c00
	s_addc_u32 s5, s5, 0
	global_store_dword v198, v197, s[4:5]
	v_mul_f32_e32 v178, v34, v150
	v_mul_f32_e32 v179, v46, v150
	v_mul_f32_e32 v180, v35, v151
	v_mul_f32_e32 v181, v47, v151
	v_mul_f32_e32 v182, v36, v152
	v_mul_f32_e32 v183, v48, v152
	v_mul_f32_e32 v184, v37, v153
	v_mul_f32_e32 v185, v49, v153
	v_exp_f32_e32 v178, v178
	v_exp_f32_e32 v179, v179
	v_exp_f32_e32 v180, v180
	v_exp_f32_e32 v181, v181
	v_exp_f32_e32 v182, v182
	v_exp_f32_e32 v183, v183
	v_exp_f32_e32 v184, v184
	v_exp_f32_e32 v185, v185
	v_mul_f32_e32 v186, v34, v38
	v_mul_f32_e32 v187, v46, v42
	v_mul_f32_e32 v188, v35, v39
	v_mul_f32_e32 v189, v47, v43
	v_mul_f32_e32 v190, v36, v40
	v_mul_f32_e32 v191, v48, v44
	v_mul_f32_e32 v192, v37, v41
	v_mul_f32_e32 v193, v49, v45
	v_fma_f32 v178, v178, v224, v224
	v_fma_f32 v179, v179, v224, v224
	v_fma_f32 v180, v180, v225, v225
	v_fma_f32 v181, v181, v225, v225
	v_fma_f32 v182, v182, v226, v226
	v_fma_f32 v183, v183, v226, v226
	v_fma_f32 v184, v184, v227, v227
	v_fma_f32 v185, v185, v227, v227
	v_rcp_f32_e32 v178, v178
	v_rcp_f32_e32 v179, v179
	v_rcp_f32_e32 v180, v180
	v_rcp_f32_e32 v181, v181
	v_rcp_f32_e32 v182, v182
	v_rcp_f32_e32 v183, v183
	v_rcp_f32_e32 v184, v184
	v_rcp_f32_e32 v185, v185
	v_mul_f32_e32 v186, v186, v178
	v_mul_f32_e32 v187, v187, v179
	v_mul_f32_e32 v188, v188, v180
	v_mul_f32_e32 v189, v189, v181
	s_add_u32 s4, s24, 0x18c000
	s_addc_u32 s5, s25, 0
	v_mul_f32_e32 v190, v190, v182
	v_mul_f32_e32 v191, v191, v183
	v_mul_f32_e32 v192, v192, v184
	v_mul_f32_e32 v193, v193, v185
	v_cvt_pk_bf16_f32 v194, v186, v187
	v_cvt_pk_bf16_f32 v195, v188, v189
	v_cvt_pk_bf16_f32 v196, v190, v191
	v_cvt_pk_bf16_f32 v197, v192, v193
	global_store_dword v198, v194, s[4:5]
	s_add_u32 s4, s4, 0x2c00
	s_addc_u32 s5, s5, 0
	global_store_dword v198, v195, s[4:5]
; __device__ __forceinline__ float fdiv(float a, float b) { return a * __builtin_amdgcn_rcpf(b); }
; __device__ __forceinline__ void gemm_tile(const Params& P, const GArgs& ga, const TileDesc& td, int wid_s) {
;     ...
;     static_for<32>([&](auto ic) __attribute__((always_inline)) {
;       EPI_IDX;
;       const float rs = rsv[idx];
;       float g0 = rs * acc[ai][0][m][0][j], u0 = rs * acc[ai][0][m][1][j];
;       float g1 = rs * acc[ai][1][m][0][j], u1 = rs * acc[ai][1][m][1][j];
;       __builtin_nontemporal_store(pack2(fdiv(g0 * u0, 1.f + __expf(-g0)), fdiv(g1 * u1, 1.f + __expf(-g1))), G + (size_t)rl * (FF / 2));
;       if constexpr ((idx & 7) == 7) __builtin_amdgcn_sched_barrier(0);
;     });
	s_add_u32 s4, s4, 0x2c00
	s_addc_u32 s5, s5, 0
	global_store_dword v198, v196, s[4:5]
	s_add_u32 s4, s4, 0x2c00
	s_addc_u32 s5, s5, 0
	global_store_dword v198, v197, s[4:5]
	v_mul_f32_e32 v178, v18, v154
	v_mul_f32_e32 v179, v30, v154
	v_mul_f32_e32 v180, v19, v155
	v_mul_f32_e32 v181, v31, v155
	v_mul_f32_e32 v182, v20, v156
	v_mul_f32_e32 v183, v32, v156
	v_mul_f32_e32 v184, v21, v157
	v_mul_f32_e32 v185, v33, v157
	v_exp_f32_e32 v178, v178
	v_exp_f32_e32 v179, v179
	v_exp_f32_e32 v180, v180
	v_exp_f32_e32 v181, v181
	v_exp_f32_e32 v182, v182
	v_exp_f32_e32 v183, v183
	v_exp_f32_e32 v184, v184
	v_exp_f32_e32 v185, v185
	v_mul_f32_e32 v186, v18, v22
	v_mul_f32_e32 v187, v30, v26
	v_mul_f32_e32 v188, v19, v23
	v_mul_f32_e32 v189, v31, v27
	v_mul_f32_e32 v190, v20, v24
	v_mul_f32_e32 v191, v32, v28
	v_mul_f32_e32 v192, v21, v25
	v_mul_f32_e32 v193, v33, v29
	v_fma_f32 v178, v178, v170, v170
	v_fma_f32 v179, v179, v170, v170
	v_fma_f32 v180, v180, v171, v171
	v_fma_f32 v181, v181, v171, v171
	v_fma_f32 v182, v182, v172, v172
	v_fma_f32 v183, v183, v172, v172
	v_fma_f32 v184, v184, v173, v173
	v_fma_f32 v185, v185, v173, v173
	v_rcp_f32_e32 v178, v178
	v_rcp_f32_e32 v179, v179
	v_rcp_f32_e32 v180, v180
	v_rcp_f32_e32 v181, v181
	v_rcp_f32_e32 v182, v182
	v_rcp_f32_e32 v183, v183
	v_rcp_f32_e32 v184, v184
	v_rcp_f32_e32 v185, v185
	v_mul_f32_e32 v186, v186, v178
	v_mul_f32_e32 v187, v187, v179
	v_mul_f32_e32 v188, v188, v180
	v_mul_f32_e32 v189, v189, v181
	s_add_u32 s4, s24, 0x1b8000
	s_addc_u32 s5, s25, 0
	v_mul_f32_e32 v190, v190, v182
	v_mul_f32_e32 v191, v191, v183
	v_mul_f32_e32 v192, v192, v184
	v_mul_f32_e32 v193, v193, v185
	v_cvt_pk_bf16_f32 v194, v186, v187
	v_cvt_pk_bf16_f32 v195, v188, v189
	v_cvt_pk_bf16_f32 v196, v190, v191
	v_cvt_pk_bf16_f32 v197, v192, v193
	global_store_dword v198, v194, s[4:5]
	s_add_u32 s4, s4, 0x2c00
	s_addc_u32 s5, s5, 0
	global_store_dword v198, v195, s[4:5]
	s_add_u32 s4, s4, 0x2c00
	s_addc_u32 s5, s5, 0
	global_store_dword v198, v196, s[4:5]
	s_add_u32 s4, s4, 0x2c00
	s_addc_u32 s5, s5, 0
	global_store_dword v198, v197, s[4:5]
	v_mul_f32_e32 v178, v2, v158
	v_mul_f32_e32 v179, v14, v158
	v_mul_f32_e32 v180, v3, v159
	v_mul_f32_e32 v181, v15, v159
	v_mul_f32_e32 v182, v4, v160
	v_mul_f32_e32 v183, v16, v160
	v_mul_f32_e32 v184, v5, v161
	v_mul_f32_e32 v185, v17, v161
	v_exp_f32_e32 v178, v178
	v_exp_f32_e32 v179, v179
	v_exp_f32_e32 v180, v180
	v_exp_f32_e32 v181, v181
	v_exp_f32_e32 v182, v182
	v_exp_f32_e32 v183, v183
	v_exp_f32_e32 v184, v184
	v_exp_f32_e32 v185, v185
	v_mul_f32_e32 v186, v2, v6
	v_mul_f32_e32 v187, v14, v10
	v_mul_f32_e32 v188, v3, v7
	v_mul_f32_e32 v189, v15, v11
	v_mul_f32_e32 v190, v4, v8
	v_mul_f32_e32 v191, v16, v12
	v_mul_f32_e32 v192, v5, v9
	v_mul_f32_e32 v193, v17, v13
	v_fma_f32 v178, v178, v174, v174
	v_fma_f32 v179, v179, v174, v174
	v_fma_f32 v180, v180, v175, v175
	v_fma_f32 v181, v181, v175, v175
	v_fma_f32 v182, v182, v176, v176
	v_fma_f32 v183, v183, v176, v176
	v_fma_f32 v184, v184, v177, v177
	v_fma_f32 v185, v185, v177, v177
	v_rcp_f32_e32 v178, v178
	v_rcp_f32_e32 v179, v179
	v_rcp_f32_e32 v180, v180
	v_rcp_f32_e32 v181, v181
	v_rcp_f32_e32 v182, v182
	v_rcp_f32_e32 v183, v183
	v_rcp_f32_e32 v184, v184
	v_rcp_f32_e32 v185, v185
	v_mul_f32_e32 v186, v186, v178
	v_mul_f32_e32 v187, v187, v179
	v_mul_f32_e32 v188, v188, v180
	v_mul_f32_e32 v189, v189, v181
	s_add_u32 s4, s24, 0x1e4000
	s_addc_u32 s5, s25, 0
	v_mul_f32_e32 v190, v190, v182
	v_mul_f32_e32 v191, v191, v183
	v_mul_f32_e32 v192, v192, v184
	v_mul_f32_e32 v193, v193, v185
	v_cvt_pk_bf16_f32 v194, v186, v187
	v_cvt_pk_bf16_f32 v195, v188, v189
	v_cvt_pk_bf16_f32 v196, v190, v191
	v_cvt_pk_bf16_f32 v197, v192, v193
	global_store_dword v198, v194, s[4:5]
	s_add_u32 s4, s4, 0x2c00
	s_addc_u32 s5, s5, 0
	global_store_dword v198, v195, s[4:5]
	s_add_u32 s4, s4, 0x2c00
	s_addc_u32 s5, s5, 0
	global_store_dword v198, v196, s[4:5]
	s_add_u32 s4, s4, 0x2c00
	s_addc_u32 s5, s5, 0
	global_store_dword v198, v197, s[4:5]
	s_branch .LBB0_290
